# rope table loop: two elements per iteration with both position loads issued together (on top of the phase-1 slot version)
# baseline (speedup 1.0000x reference)
; DI void phase_prologue(int wv, const ArgP a, LAS unsigned char* lds, int parts) {
;     ...
;     const int* pos = (const int*)a.in(1); float* cst = (float*)(ws + O_CSTAB);
;     for (int e = blockIdx.x * 512 + tid; e < S * 16; e += gridDim.x * 512) { const int t = e >> 4, i = e & 15;
;         const float invf = __builtin_amdgcn_exp2f(-(float)i * (13.287712379549449f / 16.f)); const float ang = (float)pos[t] * invf;
;         const float k = rintf(ang * 0.15915494309189535f);
;         float r = fmaf(-k, 6.28318548202514648f, ang); r = fmaf(-k, -1.7484555e-7f, r);
;         const float rr = r * 0.15915494309189535f;
;         cst[2 * e] = __builtin_amdgcn_cosf(rr); cst[2 * e + 1] = __builtin_amdgcn_sinf(rr); }
.LBB0_313:
	s_or_b64 exec, exec, s[0:1]
	s_lshl_b32 s33, s80, 9
	v_add_u32_e32 v2, s33, v15
	s_mov_b32 s0, 0x40000
	v_cmp_gt_i32_e32 vcc, s0, v2
	s_and_b64 vcc, vcc, s[94:95]
	s_and_saveexec_b64 s[0:1], vcc
	s_cbranch_execz .LBB0_316
	v_and_b32_e32 v0, 15, v14
	v_cvt_f32_ubyte0_e32 v0, v0
	s_load_dwordx2 s[2:3], s[2:3], 0x8
	v_mul_f32_e32 v0, 0xbf549a78, v0
	v_exp_f32_e32 v3, v0
	s_add_u32 s4, s12, 0x1940000
	s_addc_u32 s5, s13, 0
	s_lshl_b32 s8, s24, 9
	v_lshlrev_b32_e32 v0, 1, v2
	s_lshl_b32 s9, s24, 10
	s_mov_b64 s[6:7], 0
	s_mov_b32 s10, 0x3ffff
	s_waitcnt lgkmcnt(0)
.Lrope_loop:
	v_add_u32_e32 v8, s8, v2
	v_min_i32_e32 v9, s10, v8
	v_ashrrev_i32_e32 v4, 4, v2
	v_ashrrev_i32_e32 v10, 4, v9
	v_lshlrev_b32_e32 v4, 2, v4
	v_lshlrev_b32_e32 v10, 2, v10
	global_load_dword v4, v4, s[2:3]
	global_load_dword v10, v10, s[2:3]
	v_cmp_ge_i32_e64 s[14:15], s10, v8
	v_add_u32_e32 v20, s9, v0
	v_ashrrev_i32_e32 v1, 31, v0
	v_ashrrev_i32_e32 v21, 31, v20
	v_lshl_add_u64 v[22:23], v[0:1], 2, s[4:5]
	v_lshl_add_u64 v[16:17], v[20:21], 2, s[4:5]
	s_waitcnt vmcnt(1)
	v_cvt_f32_i32_e32 v6, v4
	v_mul_f32_e32 v5, v3, v6
	v_mul_f32_e32 v6, 0.15915494, v5
	v_rndne_f32_e32 v6, v6
	v_fmac_f32_e32 v5, 0xc0c90fdb, v6
	v_fmac_f32_e32 v5, 0x343bbd2e, v6
	v_mul_f32_e32 v5, 0.15915494, v5
	v_cos_f32_e32 v6, v5
	v_sin_f32_e32 v7, v5
	global_store_dwordx2 v[22:23], v[6:7], off
	s_waitcnt vmcnt(1)
	v_cvt_f32_i32_e32 v18, v10
	v_mul_f32_e32 v13, v3, v18
	v_mul_f32_e32 v18, 0.15915494, v13
	v_rndne_f32_e32 v18, v18
	v_fmac_f32_e32 v13, 0xc0c90fdb, v18
	v_fmac_f32_e32 v13, 0x343bbd2e, v18
	v_mul_f32_e32 v13, 0.15915494, v13
	v_cos_f32_e32 v18, v13
	v_sin_f32_e32 v19, v13
	s_and_saveexec_b64 s[16:17], s[14:15]
	global_store_dwordx2 v[16:17], v[18:19], off
	s_or_b64 exec, exec, s[16:17]
	v_add_u32_e32 v2, s8, v8
	v_add_u32_e32 v0, s9, v20
	v_cmp_lt_i32_e32 vcc, s10, v2
	s_or_b64 s[6:7], vcc, s[6:7]
	s_andn2_b64 exec, exec, s[6:7]
	s_cbranch_execnz .Lrope_loop
